# hazard hygiene: one more wait state (s_nop 0) at 7 hand-written sites where a VALU read an SGPR/VCC mask one instruction after the v_cmp/v_readlane that wrote it (the compiler pads 2)
# baseline (speedup 1.0000x reference)
.LBB0_42:
	v_readlane_b32 s4, v253, 8
	v_readlane_b32 s5, v253, 9
	s_or_b64 exec, exec, s[4:5]
	v_mov_b32_e32 v0, v204
	v_readlane_b32 s3, v253, 6
	v_ashrrev_i32_e32 v1, 6, v0
	s_nop 0
	v_add_u32_e32 v16, s3, v1
	s_mov_b32 s3, 0x8100
	v_cmp_gt_i32_e32 vcc, s3, v16
	s_and_saveexec_b64 s[8:9], vcc
	v_readlane_b32 s84, v253, 2
	s_mov_b64 s[76:77], s[16:17]
	v_readlane_b32 s85, v253, 3
	v_readlane_b32 s50, v253, 4
	s_cbranch_execz .LBB0_47
	v_mbcnt_lo_u32_b32 v1, -1, 0
	v_mbcnt_hi_u32_b32 v1, -1, v1
	v_and_b32_e32 v2, 64, v1
	v_add_u32_e32 v2, 64, v2
	v_xor_b32_e32 v3, 1, v1
	v_cmp_lt_i32_e32 vcc, v3, v2
	s_load_dwordx4 s[4:7], s[76:77], 0x0
	s_load_dwordx2 s[18:19], s[76:77], 0xc8
	v_cndmask_b32_e32 v3, v1, v3, vcc
	v_lshlrev_b32_e32 v26, 2, v3
	v_xor_b32_e32 v3, 2, v1
	v_cmp_lt_i32_e32 vcc, v3, v2
	v_ashrrev_i32_e32 v17, 31, v16
	v_and_b32_e32 v0, 63, v0
	v_cndmask_b32_e32 v3, v1, v3, vcc
	v_lshlrev_b32_e32 v27, 2, v3
	v_xor_b32_e32 v3, 4, v1
	v_cmp_lt_i32_e32 vcc, v3, v2
	s_waitcnt lgkmcnt(0)
	s_cmp_lg_u64 s[18:19], 0
	v_mov_b32_e32 v19, 0
	v_cndmask_b32_e32 v3, v1, v3, vcc
	v_lshlrev_b32_e32 v28, 2, v3
	v_xor_b32_e32 v3, 8, v1
	v_cmp_lt_i32_e32 vcc, v3, v2
	v_lshlrev_b32_e32 v18, 4, v0
	s_cselect_b64 s[16:17], -1, 0
	v_cndmask_b32_e32 v3, v1, v3, vcc
	v_lshlrev_b32_e32 v29, 2, v3
	v_xor_b32_e32 v3, 16, v1
	v_cmp_lt_i32_e32 vcc, v3, v2
	v_lshl_add_u64 v[20:21], s[18:19], 0, v[18:19]
	s_mov_b64 s[18:19], 0x5100000
	v_cndmask_b32_e32 v3, v1, v3, vcc
	v_lshlrev_b32_e32 v30, 2, v3
	v_xor_b32_e32 v3, 32, v1
	v_cmp_lt_i32_e32 vcc, v3, v2
	s_ashr_i32 s15, s14, 31
	s_mov_b64 s[10:11], 0
	v_cndmask_b32_e32 v1, v1, v3, vcc
	v_lshlrev_b64 v[2:3], 11, v[16:17]
	v_lshl_or_b32 v2, v0, 3, v2
	v_lshl_add_u64 v[2:3], s[0:1], 0, v[2:3]
	v_lshlrev_b32_e32 v31, 2, v1
	v_lshl_add_u64 v[22:23], v[2:3], 0, s[18:19]
	s_lshl_b64 s[18:19], s[14:15], 11
	s_mov_b32 s3, 0x8000
	v_mov_b32_e32 v32, s7
	v_mov_b32_e32 v33, s5
	v_mov_b32_e32 v34, s6
	v_mov_b32_e32 v35, s4
	v_lshlrev_b32_e32 v24, 4, v0
	v_mov_b32_e32 v25, v19
	s_movk_i32 s6, 0x7fff
	v_mov_b32_e32 v36, 0x358637bd
	s_mov_b32 s7, 0x800000
	s_mov_b32 s20, 0xffff0000
	s_mov_b32 s21, 0x80ff
	v_mov_b32_e32 v76, v16
	v_cmp_gt_i32_e32 vcc, s3, v76
	v_add_u32_e32 v77, 0xffff8000, v76
	s_nop 0
	v_cndmask_b32_e32 v79, v32, v33, vcc
	v_cndmask_b32_e32 v78, v34, v35, vcc
	v_cndmask_b32_e32 v77, v77, v76, vcc
	v_lshlrev_b32_e32 v76, 12, v77
	v_or_b32_e32 v76, v76, v24
	v_mov_b32_e32 v77, 0
	v_lshl_add_u64 v[78:79], v[78:79], 0, v[76:77]
	global_load_dwordx4 v[60:63], v[78:79], off
	global_load_dwordx4 v[64:67], v[78:79], off offset:1024
	global_load_dwordx4 v[72:75], v[78:79], off offset:3072
	global_load_dwordx4 v[68:71], v[78:79], off offset:2048
	s_waitcnt vmcnt(0)
	s_branch .LBB0_45

.LBB0_45:
	s_waitcnt vmcnt(4)
	v_mov_b64_e32 v[12:13], v[60:61]
	v_mov_b64_e32 v[14:15], v[62:63]
	v_mov_b64_e32 v[8:9], v[64:65]
	v_mov_b64_e32 v[10:11], v[66:67]
	v_mov_b64_e32 v[0:1], v[72:73]
	v_mov_b64_e32 v[2:3], v[74:75]
	v_mov_b64_e32 v[4:5], v[68:69]
	v_mov_b64_e32 v[6:7], v[70:71]
	v_add_u32_e32 v76, s14, v16
	v_min_i32_e32 v76, s21, v76
	v_cmp_gt_i32_e32 vcc, s3, v76
	v_add_u32_e32 v77, 0xffff8000, v76
	s_nop 0
	v_cndmask_b32_e32 v79, v32, v33, vcc
	v_cndmask_b32_e32 v78, v34, v35, vcc
	v_cndmask_b32_e32 v77, v77, v76, vcc
	v_lshlrev_b32_e32 v76, 12, v77
	v_or_b32_e32 v76, v76, v24
	v_mov_b32_e32 v77, 0
	v_lshl_add_u64 v[78:79], v[78:79], 0, v[76:77]
	global_load_dwordx4 v[60:63], v[78:79], off
	global_load_dwordx4 v[64:67], v[78:79], off offset:1024
	global_load_dwordx4 v[72:75], v[78:79], off offset:3072
	global_load_dwordx4 v[68:71], v[78:79], off offset:2048
	v_cmp_lt_i32_e32 vcc, s6, v16
	s_and_b64 s[22:23], s[16:17], vcc
	v_pk_mul_f32 v[38:39], v[14:15], v[14:15]
	v_pk_mul_f32 v[40:41], v[12:13], v[12:13]
	v_pk_mul_f32 v[42:43], v[10:11], v[10:11]
	v_pk_mul_f32 v[44:45], v[8:9], v[8:9]
	v_pk_mov_b32 v[48:49], v[40:41], v[38:39] op_sel:[1,0]
	v_mov_b32_e32 v41, v39
	v_pk_mov_b32 v[38:39], v[44:45], v[42:43] op_sel:[1,0]
	v_mov_b32_e32 v45, v43
	v_mul_f32_e32 v18, v5, v5
	v_mul_f32_e32 v46, v7, v7
	v_pk_add_f32 v[40:41], v[48:49], v[40:41]
	v_pk_add_f32 v[38:39], v[38:39], v[44:45]
	v_mul_f32_e32 v37, v0, v0
	v_mul_f32_e32 v50, v1, v1
	v_mul_f32_e32 v51, v2, v2
	v_mul_f32_e32 v52, v3, v3
	v_pk_fma_f32 v[42:43], v[4:5], v[4:5], v[18:19] op_sel_hi:[1,1,0]
	v_pk_fma_f32 v[46:47], v[6:7], v[6:7], v[46:47] op_sel_hi:[1,1,0]
	v_pk_add_f32 v[40:41], v[40:41], v[40:41] op_sel:[0,1] op_sel_hi:[1,0]
	v_pk_add_f32 v[38:39], v[38:39], v[38:39] op_sel:[0,1] op_sel_hi:[1,0]
	v_mov_b32_e32 v43, v51
	v_mov_b32_e32 v47, v52
	v_mov_b32_e32 v41, v37
	v_mov_b32_e32 v39, v50
	v_pk_add_f32 v[38:39], v[40:41], v[38:39]
	v_pk_add_f32 v[40:41], v[42:43], v[46:47]
	s_nop 0
	v_pk_add_f32 v[38:39], v[38:39], v[40:41]
	s_nop 0
	v_add_f32_e32 v18, v38, v39
	ds_bpermute_b32 v37, v26, v18
	s_waitcnt lgkmcnt(0)
	v_add_f32_e32 v18, v18, v37
	ds_bpermute_b32 v37, v27, v18
	s_waitcnt lgkmcnt(0)
	v_add_f32_e32 v18, v18, v37
	ds_bpermute_b32 v37, v28, v18
	s_waitcnt lgkmcnt(0)
	v_add_f32_e32 v18, v18, v37
	ds_bpermute_b32 v37, v29, v18
	s_waitcnt lgkmcnt(0)
	v_add_f32_e32 v18, v18, v37
	ds_bpermute_b32 v37, v30, v18
	s_waitcnt lgkmcnt(0)
	v_add_f32_e32 v37, v18, v37
	ds_bpermute_b32 v38, v31, v37
	s_and_saveexec_b64 s[4:5], s[22:23]
	s_cbranch_execz .LBB0_44
	v_mov_b32_e32 v18, v16
	v_lshlrev_b64 v[40:41], 12, v[18:19]
	v_lshl_add_u64 v[40:41], v[20:21], 0, v[40:41]
	global_store_dwordx4 v[40:41], v[12:15], off
	global_store_dwordx4 v[40:41], v[8:11], off offset:1024
	global_store_dwordx4 v[40:41], v[4:7], off offset:2048
	global_store_dwordx4 v[40:41], v[0:3], off offset:3072
	s_branch .LBB0_44

.LBB0_134:
	s_mov_b32 s4, 0xffffc300
	s_cmp_eq_u32 s75, 3
	s_cselect_b32 s4, 0xffffd980, s4
	v_mov_b32_e32 v120, 0xfffff600
	v_mov_b32_e32 v121, s4
	v_cmp_gt_i32_e32 vcc, s97, v11
	s_nop 0
	s_nop 0
	v_cndmask_b32_e32 v120, v120, v121, vcc
	v_add_u32_e32 v120, v120, v11
	s_movk_i32 s4, 0xdeff
	v_cmp_lt_i32_e32 vcc, s4, v120
	s_and_saveexec_b64 s[4:5], vcc
	s_xor_b64 s[40:41], exec, s[4:5]
	s_cbranch_execz .LBB0_170
	v_subrev_co_u32_e32 v0, vcc, 0xffffdf00, v120
	s_movk_i32 s4, 0xdeff
	s_mov_b64 s[38:39], vcc
	v_cmp_lt_u32_e32 vcc, s4, v120
	s_movk_i32 s4, 0x1080
	s_nop 0
	v_cndmask_b32_e32 v0, v120, v0, vcc
	v_add_u32_e32 v2, 0xef80, v0
	v_cmp_gt_u32_e32 vcc, s4, v0
	s_mov_b32 s4, 0xf83f
	s_nop 0
	v_cndmask_b32_e32 v3, v2, v0, vcc
	v_mul_u32_u24_sdwa v2, v3, s4 dst_sel:DWORD dst_unused:UNUSED_PAD src0_sel:WORD_0 src1_sel:DWORD
	v_lshrrev_b32_e32 v2, 25, v2
	v_mul_lo_u16_e32 v4, 0x210, v2
	v_sub_u16_e32 v3, v3, v4
	v_and_b32_e32 v4, 0x3fc, v3
	s_movk_i32 s4, 0x200
	v_cmp_ne_u32_e32 vcc, s4, v4
	s_and_saveexec_b64 s[42:43], vcc
	s_cbranch_execz .LBB0_169
	s_movk_i32 s4, 0x107f
	v_cmp_lt_u32_e32 vcc, s4, v0
	v_and_b32_e32 v20, 0xffff, v2
	s_movk_i32 s4, 0x200
	v_cndmask_b32_e64 v21, 0, 1, vcc
	v_lshlrev_b32_e32 v0, 3, v21
	global_load_dwordx2 v[18:19], v0, s[0:1] offset:32
	v_cndmask_b32_e64 v0, 0, 8, s[38:39]
	v_add_lshl_u32 v0, v0, v20, 23
	v_mov_b32_e32 v2, 0
	v_cmp_gt_u16_e32 vcc, s4, v3
	v_lshlrev_b32_e32 v8, 4, v10
	v_mov_b32_e32 v4, 0
	v_mov_b32_e32 v5, 0
	v_mov_b32_e32 v6, 0
	v_mov_b32_e32 v7, 0
	s_waitcnt vmcnt(0)
	v_lshl_add_u64 v[18:19], v[18:19], 0, v[0:1]
	v_lshlrev_b32_e32 v0, 14, v3
	v_lshl_add_u64 v[24:25], v[18:19], 0, v[0:1]
	s_and_saveexec_b64 s[48:49], vcc
	s_cbranch_execz .LBB0_138
	v_mov_b32_e32 v9, v1
	v_lshl_add_u64 v[4:5], v[24:25], 0, v[8:9]
	global_load_dwordx4 v[4:7], v[4:5], off

.LBB0_640:
	s_or_b64 exec, exec, s[54:55]
	s_mov_b32 s8, 0x8000
	v_cmp_gt_i32_e64 s[46:47], s8, v243
	v_add_u32_e32 v132, 0xffff8000, v243
	s_nop 0
	v_cndmask_b32_e64 v132, v132, v243, s[46:47]
	v_lshlrev_b32_e32 v132, 5, v132
	v_mov_b32_e32 v133, v1
	v_mov_b32_e32 v134, s28
	v_mov_b32_e32 v135, s52
	v_mov_b32_e32 v136, s4
	v_mov_b32_e32 v137, s5
	v_cndmask_b32_e64 v134, v134, v136, s[46:47]
	v_cndmask_b32_e64 v135, v135, v137, s[46:47]
	v_lshl_add_u64 v[132:133], v[134:135], 0, v[132:133]
	v_mov_b32_e32 v151, v1
	v_lshl_add_u64 v[132:133], v[132:133], 0, v[150:151]
	global_store_dword v[132:133], v131, off

.LBB0_642:
	s_waitcnt vmcnt(4)
	s_mov_b32 s8, 0x8000
	v_cmp_gt_i32_e64 s[44:45], s8, v142
	v_cmp_lt_i32_e64 s[46:47], s91, v142
	v_add_u32_e32 v152, 0xffff8000, v142
	v_mov_b64_e32 v[154:155], v[142:143]
	s_waitcnt lgkmcnt(0)
	v_mov_b64_e32 v[130:131], v[148:149]
	s_and_saveexec_b64 s[54:55], s[46:47]
	v_mov_b32_e32 v153, v1
	v_lshlrev_b64 v[130:131], 12, v[152:153]
	v_lshl_add_u64 v[130:131], s[48:49], 0, v[130:131]
	v_mov_b32_e32 v154, v142
	v_mov_b32_e32 v155, v1
	s_or_b64 exec, exec, s[54:55]
	v_lshl_add_u64 v[130:131], v[130:131], 0, v[0:1]
	v_mov_b64_e32 v[172:173], v[224:225]
	v_mov_b64_e32 v[174:175], v[226:227]
	v_mov_b64_e32 v[138:139], v[228:229]
	v_mov_b64_e32 v[140:141], v[230:231]
	s_mov_b32 s8, 0x800000
	v_pk_mul_f32 v[132:133], v[174:175], v[174:175]
	v_pk_mul_f32 v[134:135], v[172:173], v[172:173]
	s_nop 0
	v_pk_mov_b32 v[136:137], v[134:135], v[132:133] op_sel:[1,0]
	v_mov_b32_e32 v135, v133
	v_pk_add_f32 v[156:157], v[136:137], v[134:135]
	v_pk_mul_f32 v[132:133], v[140:141], v[140:141]
	v_pk_mul_f32 v[134:135], v[138:139], v[138:139]
	v_pk_add_f32 v[156:157], v[156:157], v[156:157] op_sel:[0,1] op_sel_hi:[1,0]
	v_pk_mov_b32 v[136:137], v[134:135], v[132:133] op_sel:[1,0]
	v_mov_b32_e32 v135, v133
	v_pk_add_f32 v[158:159], v[136:137], v[134:135]
	v_mov_b64_e32 v[134:135], v[232:233]
	v_mov_b64_e32 v[136:137], v[234:235]
	s_nop 0
	v_mov_b64_e32 v[130:131], v[236:237]
	v_mov_b64_e32 v[132:133], v[238:239]
	v_readlane_b32 s10, v254, 55
	s_mov_b32 s11, 0x80ff
	s_nop 0
	v_add_u32_e32 v240, s10, v142
	v_min_i32_e32 v240, s11, v240
	v_lshl_or_b32 v240, v240, 12, v0
	global_load_dwordx4 v[224:227], v240, s[100:101]
	global_load_dwordx4 v[228:231], v240, s[100:101] offset:1024
	global_load_dwordx4 v[232:235], v240, s[100:101] offset:2048
	global_load_dwordx4 v[236:239], v240, s[100:101] offset:3072
	v_pk_add_f32 v[158:159], v[158:159], v[158:159] op_sel:[0,1] op_sel_hi:[1,0]
	v_mul_f32_e32 v151, v130, v130
	v_mul_f32_e32 v153, v131, v131
	v_mov_b32_e32 v157, v151
	v_mov_b32_e32 v159, v153
	v_pk_add_f32 v[156:157], v[156:157], v[158:159]
	v_mul_f32_e32 v158, v135, v135
	v_mul_f32_e32 v176, v132, v132
	v_pk_fma_f32 v[158:159], v[134:135], v[134:135], v[158:159] op_sel_hi:[1,1,0]
	v_mul_f32_e32 v178, v133, v133
	v_mov_b32_e32 v159, v176
	v_mul_f32_e32 v176, v137, v137
	v_pk_fma_f32 v[176:177], v[136:137], v[136:137], v[176:177] op_sel_hi:[1,1,0]
	s_nop 0
	v_mov_b32_e32 v177, v178
	v_pk_add_f32 v[158:159], v[158:159], v[176:177]
	v_lshlrev_b64 v[178:179], 11, v[154:155]
	v_pk_add_f32 v[156:157], v[156:157], v[158:159]
	s_nop 0
	v_add_f32_e32 v151, v156, v157
	s_nop 1
	v_add_f32_dpp v151, v151, v151 quad_perm:[1,0,3,2] row_mask:0xf bank_mask:0xf
	s_nop 1
	v_add_f32_dpp v151, v151, v151 quad_perm:[2,3,0,1] row_mask:0xf bank_mask:0xf
	s_nop 1
	v_add_f32_dpp v151, v151, v151 row_half_mirror row_mask:0xf bank_mask:0xf
	s_nop 1
	v_add_f32_dpp v151, v151, v151 row_mirror row_mask:0xf bank_mask:0xf
	s_nop 1
	v_add_f32_dpp v151, v151, v151 row_bcast:15 row_mask:0xa bank_mask:0xf
	s_nop 1
	v_add_f32_dpp v151, v151, v151 row_bcast:31 row_mask:0xc bank_mask:0xf
	s_nop 1
	v_readlane_b32 s10, v151, 63
	s_nop 0
	s_nop 0
	v_mov_b32_e32 v151, s10
	v_fmamk_f32 v151, v151, 0x3a800000, v206
	v_cmp_gt_f32_e64 s[46:47], s8, v151
	v_mul_f32_e32 v153, 0x4b800000, v151
	s_nop 0
	v_cndmask_b32_e64 v151, v151, v153, s[46:47]
	v_rsq_f32_e32 v151, v151
	s_nop 0
	v_mul_f32_e32 v153, 0x45800000, v151
	v_cndmask_b32_e64 v176, v151, v153, s[46:47]
	v_pk_mul_f32 v[156:157], v[174:175], v[176:177] op_sel_hi:[1,0]
	v_pk_mul_f32 v[158:159], v[172:173], v[176:177] op_sel_hi:[1,0]
	v_and_b32_sdwa v172, v157, v205 dst_sel:DWORD dst_unused:UNUSED_PAD src0_sel:WORD_1 src1_sel:DWORD
	v_and_b32_sdwa v173, v159, v205 dst_sel:DWORD dst_unused:UNUSED_PAD src0_sel:WORD_1 src1_sel:DWORD
	v_and_b32_sdwa v151, v156, v205 dst_sel:DWORD dst_unused:UNUSED_PAD src0_sel:WORD_1 src1_sel:DWORD
	v_and_b32_sdwa v153, v158, v205 dst_sel:DWORD dst_unused:UNUSED_PAD src0_sel:WORD_1 src1_sel:DWORD
	v_add3_u32 v172, v157, v172, s91
	v_add3_u32 v173, v159, v173, s91
	v_add3_u32 v153, v158, v153, s91
	v_add3_u32 v151, v156, v151, s91
	v_and_b32_e32 v172, 0xffff0000, v172
	v_and_b32_e32 v174, 0xffff0000, v173
	v_or_b32_sdwa v173, v172, v151 dst_sel:DWORD dst_unused:UNUSED_PAD src0_sel:DWORD src1_sel:WORD_1
	v_or_b32_sdwa v172, v174, v153 dst_sel:DWORD dst_unused:UNUSED_PAD src0_sel:DWORD src1_sel:WORD_1
	v_lshl_add_u64 v[174:175], v[146:147], 0, v[178:179]
	v_pk_mul_f32 v[140:141], v[140:141], v[176:177] op_sel_hi:[1,0]
	v_pk_mul_f32 v[138:139], v[138:139], v[176:177] op_sel_hi:[1,0]
	global_store_dwordx2 v[174:175], v[172:173], off
	v_and_b32_sdwa v172, v141, v205 dst_sel:DWORD dst_unused:UNUSED_PAD src0_sel:WORD_1 src1_sel:DWORD
	v_and_b32_sdwa v173, v139, v205 dst_sel:DWORD dst_unused:UNUSED_PAD src0_sel:WORD_1 src1_sel:DWORD
	v_and_b32_sdwa v151, v140, v205 dst_sel:DWORD dst_unused:UNUSED_PAD src0_sel:WORD_1 src1_sel:DWORD
	v_and_b32_sdwa v153, v138, v205 dst_sel:DWORD dst_unused:UNUSED_PAD src0_sel:WORD_1 src1_sel:DWORD
	v_add3_u32 v172, v141, v172, s91
	v_add3_u32 v173, v139, v173, s91
	v_add3_u32 v153, v138, v153, s91
	v_add3_u32 v151, v140, v151, s91
	v_and_b32_e32 v172, 0xffff0000, v172
	v_and_b32_e32 v177, 0xffff0000, v173
	v_or_b32_sdwa v173, v172, v151 dst_sel:DWORD dst_unused:UNUSED_PAD src0_sel:DWORD src1_sel:WORD_1
	v_or_b32_sdwa v172, v177, v153 dst_sel:DWORD dst_unused:UNUSED_PAD src0_sel:DWORD src1_sel:WORD_1
	v_pk_mul_f32 v[136:137], v[136:137], v[176:177] op_sel_hi:[1,0]
	v_pk_mul_f32 v[134:135], v[134:135], v[176:177] op_sel_hi:[1,0]
	global_store_dwordx2 v[174:175], v[172:173], off offset:512
	v_and_b32_sdwa v172, v137, v205 dst_sel:DWORD dst_unused:UNUSED_PAD src0_sel:WORD_1 src1_sel:DWORD
	v_and_b32_sdwa v173, v135, v205 dst_sel:DWORD dst_unused:UNUSED_PAD src0_sel:WORD_1 src1_sel:DWORD
	v_and_b32_sdwa v151, v136, v205 dst_sel:DWORD dst_unused:UNUSED_PAD src0_sel:WORD_1 src1_sel:DWORD
	v_and_b32_sdwa v153, v134, v205 dst_sel:DWORD dst_unused:UNUSED_PAD src0_sel:WORD_1 src1_sel:DWORD
	v_add3_u32 v172, v137, v172, s91
	v_add3_u32 v173, v135, v173, s91
	v_add3_u32 v153, v134, v153, s91
	v_add3_u32 v151, v136, v151, s91
	v_and_b32_e32 v172, 0xffff0000, v172
	v_and_b32_e32 v177, 0xffff0000, v173
	v_or_b32_sdwa v173, v172, v151 dst_sel:DWORD dst_unused:UNUSED_PAD src0_sel:DWORD src1_sel:WORD_1
	v_or_b32_sdwa v172, v177, v153 dst_sel:DWORD dst_unused:UNUSED_PAD src0_sel:DWORD src1_sel:WORD_1
	v_pk_mul_f32 v[132:133], v[132:133], v[176:177] op_sel_hi:[1,0]
	v_pk_mul_f32 v[130:131], v[130:131], v[176:177] op_sel_hi:[1,0]
	global_store_dwordx2 v[174:175], v[172:173], off offset:1024
	v_and_b32_sdwa v172, v133, v205 dst_sel:DWORD dst_unused:UNUSED_PAD src0_sel:WORD_1 src1_sel:DWORD
	v_and_b32_sdwa v173, v131, v205 dst_sel:DWORD dst_unused:UNUSED_PAD src0_sel:WORD_1 src1_sel:DWORD
	v_and_b32_sdwa v151, v132, v205 dst_sel:DWORD dst_unused:UNUSED_PAD src0_sel:WORD_1 src1_sel:DWORD
	v_and_b32_sdwa v153, v130, v205 dst_sel:DWORD dst_unused:UNUSED_PAD src0_sel:WORD_1 src1_sel:DWORD
	v_add3_u32 v172, v133, v172, s91
	v_add3_u32 v173, v131, v173, s91
	v_add3_u32 v153, v130, v153, s91
	v_add3_u32 v151, v132, v151, s91
	v_and_b32_e32 v172, 0xffff0000, v172
	v_and_b32_e32 v176, 0xffff0000, v173
	v_or_b32_sdwa v173, v172, v151 dst_sel:DWORD dst_unused:UNUSED_PAD src0_sel:DWORD src1_sel:WORD_1
	v_or_b32_sdwa v172, v176, v153 dst_sel:DWORD dst_unused:UNUSED_PAD src0_sel:DWORD src1_sel:WORD_1
	global_store_dwordx2 v[174:175], v[172:173], off offset:1536
	v_pk_mul_f32 v[180:181], v[2:3], v[158:159]
	v_pk_mul_f32 v[182:183], v[18:19], v[158:159]
	v_pk_mul_f32 v[184:185], v[34:35], v[158:159]
	v_pk_mul_f32 v[186:187], v[50:51], v[158:159]
	v_pk_fma_f32 v[180:181], v[4:5], v[156:157], v[180:181]
	v_pk_fma_f32 v[182:183], v[20:21], v[156:157], v[182:183]
	v_pk_fma_f32 v[184:185], v[36:37], v[156:157], v[184:185]
	v_pk_fma_f32 v[186:187], v[52:53], v[156:157], v[186:187]
	v_pk_fma_f32 v[180:181], v[6:7], v[138:139], v[180:181]
	v_pk_fma_f32 v[182:183], v[22:23], v[138:139], v[182:183]
	v_pk_fma_f32 v[184:185], v[38:39], v[138:139], v[184:185]
	v_pk_fma_f32 v[186:187], v[54:55], v[138:139], v[186:187]
	v_pk_fma_f32 v[180:181], v[8:9], v[140:141], v[180:181]
	v_pk_fma_f32 v[182:183], v[24:25], v[140:141], v[182:183]
	v_pk_fma_f32 v[184:185], v[40:41], v[140:141], v[184:185]
	v_pk_fma_f32 v[186:187], v[56:57], v[140:141], v[186:187]
	v_pk_fma_f32 v[180:181], v[10:11], v[134:135], v[180:181]
	v_pk_fma_f32 v[182:183], v[26:27], v[134:135], v[182:183]
	v_pk_fma_f32 v[184:185], v[42:43], v[134:135], v[184:185]
	v_pk_fma_f32 v[186:187], v[58:59], v[134:135], v[186:187]
	v_pk_fma_f32 v[180:181], v[12:13], v[136:137], v[180:181]
	v_pk_fma_f32 v[182:183], v[28:29], v[136:137], v[182:183]
	v_pk_fma_f32 v[184:185], v[44:45], v[136:137], v[184:185]
	v_pk_fma_f32 v[186:187], v[60:61], v[136:137], v[186:187]
	v_pk_fma_f32 v[180:181], v[14:15], v[130:131], v[180:181]
	v_pk_fma_f32 v[182:183], v[30:31], v[130:131], v[182:183]
	v_pk_fma_f32 v[184:185], v[46:47], v[130:131], v[184:185]
	v_pk_fma_f32 v[186:187], v[62:63], v[130:131], v[186:187]
	v_pk_fma_f32 v[180:181], v[16:17], v[132:133], v[180:181]
	v_pk_fma_f32 v[182:183], v[32:33], v[132:133], v[182:183]
	v_pk_fma_f32 v[184:185], v[48:49], v[132:133], v[184:185]
	v_pk_fma_f32 v[186:187], v[64:65], v[132:133], v[186:187]
	v_add_f32_e32 v151, v180, v181
	v_add_f32_e32 v153, v182, v183
	v_add_f32_e32 v172, v184, v185
	v_add_f32_e32 v173, v186, v187
	v_pk_mul_f32 v[180:181], v[66:67], v[158:159]
	v_pk_mul_f32 v[182:183], v[82:83], v[158:159]
	v_pk_mul_f32 v[184:185], v[98:99], v[158:159]
	v_pk_mul_f32 v[186:187], v[114:115], v[158:159]
	v_pk_fma_f32 v[180:181], v[68:69], v[156:157], v[180:181]
	v_pk_fma_f32 v[182:183], v[84:85], v[156:157], v[182:183]
	v_pk_fma_f32 v[184:185], v[100:101], v[156:157], v[184:185]
	v_pk_fma_f32 v[186:187], v[116:117], v[156:157], v[186:187]
	v_pk_fma_f32 v[180:181], v[70:71], v[138:139], v[180:181]
	v_pk_fma_f32 v[182:183], v[86:87], v[138:139], v[182:183]
	v_pk_fma_f32 v[184:185], v[102:103], v[138:139], v[184:185]
	v_pk_fma_f32 v[186:187], v[118:119], v[138:139], v[186:187]
	v_pk_fma_f32 v[180:181], v[72:73], v[140:141], v[180:181]
	v_pk_fma_f32 v[182:183], v[88:89], v[140:141], v[182:183]
	v_pk_fma_f32 v[184:185], v[104:105], v[140:141], v[184:185]
	v_pk_fma_f32 v[186:187], v[120:121], v[140:141], v[186:187]
	v_pk_fma_f32 v[180:181], v[74:75], v[134:135], v[180:181]
	v_pk_fma_f32 v[182:183], v[90:91], v[134:135], v[182:183]
	v_pk_fma_f32 v[184:185], v[106:107], v[134:135], v[184:185]
	v_pk_fma_f32 v[186:187], v[122:123], v[134:135], v[186:187]
	v_pk_fma_f32 v[180:181], v[76:77], v[136:137], v[180:181]
	v_pk_fma_f32 v[182:183], v[92:93], v[136:137], v[182:183]
	v_pk_fma_f32 v[184:185], v[108:109], v[136:137], v[184:185]
	v_pk_fma_f32 v[186:187], v[124:125], v[136:137], v[186:187]
	v_pk_fma_f32 v[180:181], v[78:79], v[130:131], v[180:181]
	v_pk_fma_f32 v[182:183], v[94:95], v[130:131], v[182:183]
	v_pk_fma_f32 v[184:185], v[110:111], v[130:131], v[184:185]
	v_pk_fma_f32 v[186:187], v[126:127], v[130:131], v[186:187]
	v_pk_fma_f32 v[180:181], v[80:81], v[132:133], v[180:181]
	v_pk_fma_f32 v[182:183], v[96:97], v[132:133], v[182:183]
	v_pk_fma_f32 v[184:185], v[112:113], v[132:133], v[184:185]
	v_pk_fma_f32 v[186:187], v[128:129], v[132:133], v[186:187]
	v_add_f32_e32 v174, v180, v181
	v_add_f32_e32 v175, v182, v183
	v_add_f32_e32 v176, v184, v185
	v_add_f32_e32 v130, v186, v187
	v_cndmask_b32_e32 v131, v151, v174, vcc
	v_cndmask_b32_e32 v132, v153, v175, vcc
	v_cndmask_b32_e32 v133, v172, v176, vcc
	v_cndmask_b32_e32 v134, v173, v130, vcc
	ds_bpermute_b32 v131, v166, v131
	ds_bpermute_b32 v132, v166, v132
	ds_bpermute_b32 v133, v166, v133
	ds_bpermute_b32 v134, v166, v134
	v_cndmask_b32_e32 v180, v174, v151, vcc
	v_cndmask_b32_e32 v181, v175, v153, vcc
	v_cndmask_b32_e32 v182, v176, v172, vcc
	v_cndmask_b32_e32 v183, v130, v173, vcc
	s_waitcnt lgkmcnt(0)
	v_add_f32_e32 v131, v180, v131
	v_add_f32_e32 v132, v181, v132
	v_add_f32_e32 v133, v182, v133
	v_add_f32_e32 v130, v183, v134
	v_cndmask_b32_e64 v134, v131, v133, s[38:39]
	v_cndmask_b32_e64 v131, v133, v131, s[38:39]
	ds_bpermute_b32 v133, v167, v134
	s_waitcnt lgkmcnt(0)
	v_add_f32_e32 v131, v131, v133
	v_cndmask_b32_e64 v133, v132, v130, s[38:39]
	v_cndmask_b32_e64 v130, v130, v132, s[38:39]
	ds_bpermute_b32 v132, v167, v133
	s_waitcnt lgkmcnt(0)
	v_add_f32_e32 v130, v130, v132
	v_cndmask_b32_e64 v132, v131, v130, s[40:41]
	v_cndmask_b32_e64 v130, v130, v131, s[40:41]
	ds_bpermute_b32 v131, v168, v132
	s_waitcnt lgkmcnt(0)
	v_add_f32_e32 v130, v130, v131
	ds_bpermute_b32 v131, v169, v130
	s_waitcnt lgkmcnt(0)
	v_add_f32_e32 v130, v130, v131
	ds_bpermute_b32 v131, v170, v130
	s_waitcnt lgkmcnt(0)
	v_add_f32_e32 v130, v130, v131
	ds_bpermute_b32 v131, v171, v130
	s_waitcnt lgkmcnt(0)
	v_add_f32_e32 v130, v130, v131
	v_add_f32_e32 v130, v130, v241
	v_cmp_eq_u32_e64 s[46:47], s96, v244
	s_add_i32 s96, s96, 1
	s_nop 0
	v_cndmask_b32_e64 v242, v242, v130, s[46:47]
	v_cndmask_b32_e64 v243, v243, v142, s[46:47]
	s_cmp_lt_u32 s96, 8
	s_cbranch_scc1 .LBB0_641
